# cross-half-step K-fragment prefetch: the six opening K-fragment reads of the second half-step (pair 0 in a third register set) are issued from the first half-step's tail, ahead of its scaling VALU
# speedup vs baseline: 1.0049x; 1.0049x over previous
; __device__ __forceinline__ void partialSM(f32x16& p0, f32x16& p1, float& m_reg, float& mn, float& alpha, bool rs) {
;     ...
;     const float mnL = rs ? -mn * C2 : -__builtin_inff();
;     for (int r = 0; r < 16; ++r) p0[r] = fmaf(p0[r], C2, mnL); for (int r = 0; r < 16; ++r) p1[r] = fmaf(p1[r], C2, mnL);
;     for (int r = 0; r < 16; ++r) p0[r] = __builtin_amdgcn_exp2f(p0[r]);
; template <int KB>
; __device__ __forceinline__ void qkt(f32x16& p0, f32x16& p1, const char* K_lds, int r32, int hi, const bf16x8* qr) {
;     p0 = f32x16{}; p1 = f32x16{};
;     const char* kb[4];
; #pragma unroll
;     for (int dd = 0; dd < 4; ++dd) kb[dd] = K_lds + KB * SHM_K + KSWZ(r32, (dd * 16 + hi * 8) * 2);
; #pragma unroll
;     for (int d0 = 0; d0 < 8; ++d0) { const char* a = kb[d0 & 3] + (d0 >> 2) * 128;
;         bf16x8 b0 = *reinterpret_cast<const bf16x8*>(a);
;         bf16x8 b1 = *reinterpret_cast<const bf16x8*>(a + 32 * 256);
;         p0 = __builtin_amdgcn_mfma_f32_32x32x16_bf16(b0, qr[d0], p0, 0, 0, 0);
;         p1 = __builtin_amdgcn_mfma_f32_32x32x16_bf16(b1, qr[d0], p1, 0, 0, 0); }
.LBB0_95:
	ds_read_b128 v[100:103], v169 offset:32768
	ds_read_b128 v[136:139], v169 offset:40960
	ds_read_b128 v[172:175], v193 offset:32768
	ds_read_b128 v[228:231], v193 offset:40960
	ds_read_b128 v[234:237], v194 offset:32768
	ds_read_b128 v[238:241], v194 offset:40960
	v_cndmask_b32_e64 v179, v148, v198, s[42:43]
	v_mul_f32_e32 v148, 0xbe0293ee, v179
	v_cndmask_b32_e64 v180, v220, v148, s[40:41]
	v_fmamk_f32 v82, v82, 0x3e0293ee, v180
	v_fmamk_f32 v83, v83, 0x3e0293ee, v180
	v_fmamk_f32 v84, v84, 0x3e0293ee, v180
	v_fmamk_f32 v85, v85, 0x3e0293ee, v180
	v_fmamk_f32 v86, v86, 0x3e0293ee, v180
	v_fmamk_f32 v87, v87, 0x3e0293ee, v180
	v_fmamk_f32 v88, v88, 0x3e0293ee, v180
	v_fmamk_f32 v89, v89, 0x3e0293ee, v180
	v_fmamk_f32 v90, v90, 0x3e0293ee, v180
	v_fmamk_f32 v91, v91, 0x3e0293ee, v180
	v_fmamk_f32 v92, v92, 0x3e0293ee, v180
	v_fmamk_f32 v93, v93, 0x3e0293ee, v180
	v_fmamk_f32 v94, v94, 0x3e0293ee, v180
	v_fmamk_f32 v95, v95, 0x3e0293ee, v180
	v_fmamk_f32 v96, v96, 0x3e0293ee, v180
	v_fmamk_f32 v97, v97, 0x3e0293ee, v180
	v_exp_f32_e32 v148, v82
	v_exp_f32_e32 v163, v83
	v_exp_f32_e32 v149, v84
	v_exp_f32_e32 v162, v85
	v_exp_f32_e32 v150, v86
	v_exp_f32_e32 v161, v87
	v_exp_f32_e32 v151, v88
	v_exp_f32_e32 v160, v89
	v_exp_f32_e32 v152, v90
	v_exp_f32_e32 v159, v91
	v_exp_f32_e32 v153, v92
	v_exp_f32_e32 v158, v93
	v_exp_f32_e32 v154, v94
	v_exp_f32_e32 v157, v95
	v_exp_f32_e32 v155, v96
	v_exp_f32_e32 v156, v97
	v_fmamk_f32 v203, v73, 0x3e0293ee, v180
	v_fmamk_f32 v204, v74, 0x3e0293ee, v180
	v_fmamk_f32 v208, v66, 0x3e0293ee, v180
	v_fmamk_f32 v209, v67, 0x3e0293ee, v180
	v_fmamk_f32 v223, v68, 0x3e0293ee, v180
	v_fmamk_f32 v224, v69, 0x3e0293ee, v180
	v_fmamk_f32 v225, v70, 0x3e0293ee, v180
	v_fmamk_f32 v198, v71, 0x3e0293ee, v180
	v_fmamk_f32 v201, v72, 0x3e0293ee, v180
	v_fmamk_f32 v205, v75, 0x3e0293ee, v180
	v_fmamk_f32 v206, v76, 0x3e0293ee, v180
	v_fmamk_f32 v207, v77, 0x3e0293ee, v180
	v_fmamk_f32 v181, v78, 0x3e0293ee, v180
	v_fmamk_f32 v226, v79, 0x3e0293ee, v180
	v_fmamk_f32 v227, v80, 0x3e0293ee, v180
	v_fmac_f32_e32 v180, 0x3e0293ee, v81
	s_waitcnt lgkmcnt(0)
	v_exp_f32_e32 v198, v198
	v_exp_f32_e32 v201, v201
	v_exp_f32_e32 v214, v204
	v_exp_f32_e32 v205, v205
	v_exp_f32_e32 v206, v206
	v_exp_f32_e32 v207, v207
	v_exp_f32_e32 v181, v181
	v_exp_f32_e32 v215, v226
	v_exp_f32_e32 v216, v227
	v_exp_f32_e32 v180, v180
	v_exp_f32_e32 v218, v209
	v_exp_f32_e32 v209, v203
	v_add_f32_e32 v203, 0, v148
	v_add_f32_e32 v203, v163, v203
	v_add_f32_e32 v203, v149, v203
	v_add_f32_e32 v203, v162, v203
	v_add_f32_e32 v203, v150, v203
	v_add_f32_e32 v203, v161, v203
	v_add_f32_e32 v203, v151, v203
	v_add_f32_e32 v203, v160, v203
	s_waitcnt lgkmcnt(5)
	v_mfma_f32_32x32x16_bf16 v[82:97], v[100:103], v[132:135], 0
	v_add_f32_e32 v203, v152, v203
	v_add_f32_e32 v203, v159, v203
	v_add_f32_e32 v203, v153, v203
	v_add_f32_e32 v203, v158, v203
	s_waitcnt lgkmcnt(4)
	v_mfma_f32_32x32x16_bf16 v[66:81], v[136:139], v[132:135], 0
	v_exp_f32_e32 v217, v208
	v_add_f32_e32 v203, v154, v203
	v_add_f32_e32 v203, v157, v203
	v_exp_f32_e32 v219, v223
	s_waitcnt lgkmcnt(3)
	v_mfma_f32_32x32x16_bf16 v[82:97], v[172:175], v[128:131], v[82:97]
	v_add_f32_e32 v203, v155, v203
	v_exp_f32_e32 v222, v224
	v_add_f32_e32 v203, v156, v203
	v_exp_f32_e32 v208, v225
	s_waitcnt lgkmcnt(2)
	v_mfma_f32_32x32x16_bf16 v[66:81], v[228:231], v[128:131], v[66:81]
	v_add_f32_e32 v203, v217, v203
	v_add_f32_e32 v203, v218, v203
	v_add_f32_e32 v203, v219, v203
	v_add_f32_e32 v203, v222, v203
	ds_read_b128 v[172:175], v195 offset:32768
	ds_read_b128 v[228:231], v195 offset:40960
	s_waitcnt lgkmcnt(3)
	v_mfma_f32_32x32x16_bf16 v[82:97], v[234:237], v[124:127], v[82:97]
	v_add_f32_e32 v203, v208, v203
	v_add_f32_e32 v203, v198, v203
	v_add_f32_e32 v203, v201, v203
	v_add_f32_e32 v203, v209, v203
	s_waitcnt lgkmcnt(2)
; __device__ __forceinline__ void finishSM(f32x16& p0, f32x16& p1, float alpha, float& l_reg, bf16x8& pa0, bf16x8& pa1, bf16x8& pa2, bf16x8& pa3) {
;     ...
;     PK4(p0, 0, pa0); PK4(p0, 8, pa1); PK4(p1, 0, pa2); PK4(p1, 8, pa3);
; template <int KB>
; __device__ __forceinline__ void qkt(f32x16& p0, f32x16& p1, const char* K_lds, int r32, int hi, const bf16x8* qr) {
;     p0 = f32x16{}; p1 = f32x16{};
;     const char* kb[4];
; #pragma unroll
;     for (int dd = 0; dd < 4; ++dd) kb[dd] = K_lds + KB * SHM_K + KSWZ(r32, (dd * 16 + hi * 8) * 2);
; #pragma unroll
;     for (int d0 = 0; d0 < 8; ++d0) { const char* a = kb[d0 & 3] + (d0 >> 2) * 128;
;         bf16x8 b0 = *reinterpret_cast<const bf16x8*>(a);
;         bf16x8 b1 = *reinterpret_cast<const bf16x8*>(a + 32 * 256);
;         p0 = __builtin_amdgcn_mfma_f32_32x32x16_bf16(b0, qr[d0], p0, 0, 0, 0);
;         p1 = __builtin_amdgcn_mfma_f32_32x32x16_bf16(b1, qr[d0], p1, 0, 0, 0); }
; }
	v_mfma_f32_32x32x16_bf16 v[66:81], v[238:241], v[124:127], v[66:81]
	v_add_f32_e32 v203, v214, v203
	v_add_f32_e32 v203, v205, v203
	v_add_f32_e32 v203, v206, v203
	v_add_f32_e32 v203, v207, v203
	ds_read_b128 v[234:237], v169 offset:32896
	ds_read_b128 v[238:241], v169 offset:41088
	s_waitcnt lgkmcnt(3)
	v_mfma_f32_32x32x16_bf16 v[82:97], v[172:175], v[120:123], v[82:97]
	v_add_f32_e32 v203, v181, v203
	v_add_f32_e32 v203, v215, v203
	v_add_f32_e32 v203, v216, v203
	v_add_f32_e32 v203, v180, v203
	s_waitcnt lgkmcnt(2)
	v_mfma_f32_32x32x16_bf16 v[66:81], v[228:231], v[120:123], v[66:81]
	v_mov_b32_e32 v204, v203
	v_cvt_pk_bf16_f32 v148, v148, v163
	v_cvt_pk_bf16_f32 v149, v149, v162
	v_cvt_pk_bf16_f32 v150, v150, v161
	ds_read_b128 v[172:175], v193 offset:32896
	ds_read_b128 v[228:231], v193 offset:41088
	s_waitcnt lgkmcnt(3)
	v_mfma_f32_32x32x16_bf16 v[82:97], v[234:237], v[116:119], v[82:97]
	v_cvt_pk_bf16_f32 v151, v151, v160
	v_cvt_pk_bf16_f32 v152, v152, v159
	v_cvt_pk_bf16_f32 v153, v153, v158
	v_cvt_pk_bf16_f32 v154, v154, v157
	s_waitcnt lgkmcnt(2)
	v_mfma_f32_32x32x16_bf16 v[66:81], v[238:241], v[116:119], v[66:81]
	v_cvt_pk_bf16_f32 v155, v155, v156
	v_cvt_pk_bf16_f32 v156, v217, v218
	v_cvt_pk_bf16_f32 v157, v219, v222
	ds_read_b128 v[234:237], v194 offset:32896
	ds_read_b128 v[238:241], v194 offset:41088
	s_waitcnt lgkmcnt(3)
	v_mfma_f32_32x32x16_bf16 v[82:97], v[172:175], v[112:115], v[82:97]
	v_cvt_pk_bf16_f32 v158, v208, v198
	v_cvt_pk_bf16_f32 v159, v201, v209
	v_cvt_pk_bf16_f32 v160, v214, v205
	s_waitcnt lgkmcnt(2)
	v_mfma_f32_32x32x16_bf16 v[66:81], v[228:231], v[112:115], v[66:81]
	v_cvt_pk_bf16_f32 v161, v206, v207
	v_cvt_pk_bf16_f32 v162, v181, v215
	v_cvt_pk_bf16_f32 v163, v216, v180
	ds_read_b128 v[172:175], v195 offset:32896
	ds_read_b128 v[228:231], v195 offset:41088
	ds_read_b64_tr_b16 v[206:207], v185 offset:0x5000
	ds_read_b64_tr_b16 v[208:209], v185 offset:0x5800
	ds_read_b64_tr_b16 v[224:225], v185 offset:0x6000
	ds_read_b64_tr_b16 v[226:227], v185 offset:0x6800
	s_waitcnt lgkmcnt(7)
	v_mfma_f32_32x32x16_bf16 v[82:97], v[234:237], v[108:111], v[82:97]
	s_nop 1
	v_permlane32_swap_b32_e32 v203, v204
	v_permlane32_swap_b32_e32 v148, v150
	v_permlane32_swap_b32_e32 v149, v151
	s_waitcnt lgkmcnt(6)
	v_mfma_f32_32x32x16_bf16 v[66:81], v[238:241], v[108:111], v[66:81]
	v_permlane32_swap_b32_e32 v152, v154
	v_permlane32_swap_b32_e32 v153, v155
	v_permlane32_swap_b32_e32 v156, v158
	s_waitcnt lgkmcnt(5)
	v_mfma_f32_32x32x16_bf16 v[82:97], v[172:175], v[104:107], v[82:97]
	v_permlane32_swap_b32_e32 v157, v159
	v_permlane32_swap_b32_e32 v160, v162
	v_permlane32_swap_b32_e32 v161, v163
	s_waitcnt lgkmcnt(4)
	v_mfma_f32_32x32x16_bf16 v[66:81], v[228:231], v[104:107], v[66:81]
	ds_read_b64_tr_b16 v[172:173], v185 offset:0x4000
	ds_read_b64_tr_b16 v[174:175], v185 offset:0x4800
	ds_read_b64_tr_b16 v[228:229], v185 offset:0x7000
	ds_read_b64_tr_b16 v[230:231], v185 offset:0x7800
	s_cmp_lt_u32 s3, s2
	s_cselect_b64 s[22:23], -1, 0
	s_cmp_ge_u32 s3, s2
	s_sub_i32 m0, 0, s100
	s_max_i32 m0, m0, 0
	s_add_i32 m0, m0, s32
	s_add_i32 m0, m0, s32
	s_sub_i32 m0, m0, 0xc000
	s_nop 0
	global_load_lds_dwordx4 v[248:249], off
	s_add_i32 m0, m0, 896
	s_nop 0
	global_load_lds_dwordx4 v[248:249], off offset:128
	v_lshl_add_u64 v[248:249], v[248:249], 0, v[250:251]
	s_add_i32 m0, s3, 1
	s_cmp_ge_u32 m0, s2
	s_cbranch_scc1 .LBB0_97
	s_max_i32 m0, s100, 0
	s_add_i32 m0, m0, s32
	s_nop 0
	global_load_lds_dwordx4 v[244:245], off
	s_add_i32 m0, m0, 0x2000
	s_nop 0
	global_load_lds_dwordx4 v[246:247], off
	v_lshl_add_u64 v[244:245], v[244:245], 0, v[250:251]
	v_lshl_add_u64 v[246:247], v[246:247], 0, v[250:251]
